# gdn_prep forward substitution restructured: diagonal-block inverses computed once (four waves in parallel), then per-wave register-resident f32 MFMA chain for 32 columns; 2 barriers instead of 8
# speedup vs baseline: 1.0195x; 1.0084x over previous
; DI void phase_gdn_prep(const Params& p, int l, char* smem) {
;     ...
;         for (int rb = 0; rb < 4; ++rb) {
;             if (rb > 0) {
;                 const int j = tid & 127, rh = tid >> 7;
;                 float* X = (j < 64) ? sv : sk; const int col = j & 63;
;                 const int r0 = rb * 16 + rh * 8;
;                 float a[8];
; #pragma unroll
;                 for (int i = 0; i < 8; ++i) a[i] = 0.f;
;                 for (int s4 = 0; s4 < rb * 16; s4 += 4) {
;                     const float x0 = X[(s4 + 0) * 65 + col], x1 = X[(s4 + 1) * 65 + col], x2 = X[(s4 + 2) * 65 + col], x3 = X[(s4 + 3) * 65 + col];
; #pragma unroll
;                     for (int i = 0; i < 8; ++i) {
;                         const f32x4 lv = *(const f32x4*)(sL + (r0 + i) * 64 + s4);
;                         a[i] += lv[0] * x0 + lv[1] * x1 + lv[2] * x2 + lv[3] * x3;
;                     }
;                 }
; #pragma unroll
;                 for (int i = 0; i < 8; ++i) X[(r0 + i) * 65 + col] -= a[i];
;                 __syncthreads();
;             }
;             if (tid < 128) {
;                 float* X = (tid < 64) ? sv : sk; const int col = tid & 63;
;                 float x[16];
; #pragma unroll
;                 for (int i = 0; i < 16; ++i) x[i] = X[(rb * 16 + i) * 65 + col];
; #pragma unroll
;                 for (int i = 1; i < 16; ++i) {
;                     const float* Lr = sL + (rb * 16 + i) * 64 + rb * 16;
;                     float acc = x[i];
; #pragma unroll
;                     for (int s2 = 0; s2 < i; ++s2) acc -= Lr[s2] * x[s2];
;                     x[i] = acc;
;                 }
; #pragma unroll
;                 for (int i = 1; i < 16; ++i) X[(rb * 16 + i) * 65 + col] = x[i];
;             }
;             __syncthreads();
;         }
.LBB0_333:
	s_or_b64 exec, exec, s[4:5]
	v_lshrrev_b32_e32 v185, 6, v40
	v_and_b32_e32 v191, 15, v62
	v_lshrrev_b32_e32 v208, 4, v62
	v_mul_u32_u24_e32 v186, 0x1040, v185
	v_lshl_add_u32 v186, v191, 2, v186
	v_add_u32_e32 v186, 0xc300, v186
	ds_read_b32 v36, v186 offset:256
	ds_read_b32 v37, v186 offset:512
	ds_read_b32 v38, v186 offset:768
	ds_read_b32 v39, v186 offset:1024
	ds_read_b32 v58, v186 offset:1280
	ds_read_b32 v59, v186 offset:1536
	ds_read_b32 v60, v186 offset:1792
	ds_read_b32 v61, v186 offset:2048
	ds_read_b32 v230, v186 offset:2304
	ds_read_b32 v231, v186 offset:2560
	ds_read_b32 v232, v186 offset:2816
	ds_read_b32 v233, v186 offset:3072
	ds_read_b32 v234, v186 offset:3328
	ds_read_b32 v235, v186 offset:3584
	ds_read_b32 v236, v186 offset:3840
	v_cmp_eq_u32_e64 s[4:5], 0, v191
	v_cmp_eq_u32_e64 s[6:7], 1, v191
	v_cmp_eq_u32_e64 s[86:87], 2, v191
	v_cndmask_b32_e64 v192, 0, 1.0, s[4:5]
	v_cmp_eq_u32_e64 s[4:5], 3, v191
	v_cndmask_b32_e64 v193, 0, 1.0, s[6:7]
	v_cmp_eq_u32_e64 s[6:7], 4, v191
	v_cndmask_b32_e64 v194, 0, 1.0, s[86:87]
	v_cmp_eq_u32_e64 s[86:87], 5, v191
	v_cndmask_b32_e64 v195, 0, 1.0, s[4:5]
	v_cmp_eq_u32_e64 s[4:5], 6, v191
	v_cndmask_b32_e64 v196, 0, 1.0, s[6:7]
	v_cmp_eq_u32_e64 s[6:7], 7, v191
	v_cndmask_b32_e64 v197, 0, 1.0, s[86:87]
	v_cmp_eq_u32_e64 s[86:87], 8, v191
	v_cndmask_b32_e64 v198, 0, 1.0, s[4:5]
	v_cmp_eq_u32_e64 s[4:5], 9, v191
	v_cndmask_b32_e64 v199, 0, 1.0, s[6:7]
	v_cmp_eq_u32_e64 s[6:7], 10, v191
	v_cndmask_b32_e64 v200, 0, 1.0, s[86:87]
	v_cmp_eq_u32_e64 s[86:87], 11, v191
	v_cndmask_b32_e64 v201, 0, 1.0, s[4:5]
	v_cmp_eq_u32_e64 s[4:5], 12, v191
	v_cndmask_b32_e64 v202, 0, 1.0, s[6:7]
	v_cmp_eq_u32_e64 s[6:7], 13, v191
	v_cndmask_b32_e64 v203, 0, 1.0, s[86:87]
	v_cmp_eq_u32_e64 s[86:87], 14, v191
	v_cndmask_b32_e64 v204, 0, 1.0, s[4:5]
	v_cmp_eq_u32_e64 s[4:5], 15, v191
	v_cndmask_b32_e64 v205, 0, 1.0, s[6:7]
	v_cndmask_b32_e64 v206, 0, 1.0, s[86:87]
	v_cndmask_b32_e64 v207, 0, 1.0, s[4:5]
	s_waitcnt lgkmcnt(0)
	s_nop 1
	v_readlane_b32 s98, v36, 0
	v_readlane_b32 s99, v37, 0
	v_readlane_b32 s100, v37, 1
	v_readlane_b32 s101, v38, 0
	v_fma_f32 v193, -v192, s98, v193
	v_readlane_b32 s6, v39, 0
	v_fma_f32 v194, -v192, s99, v194
	v_readlane_b32 s7, v38, 1
	v_fma_f32 v194, -v193, s100, v194
	v_readlane_b32 s98, v39, 1
	v_fma_f32 v195, -v192, s101, v195
	v_readlane_b32 s99, v38, 2
	v_fma_f32 v196, -v192, s6, v196
	v_readlane_b32 s100, v39, 2
	v_fma_f32 v195, -v193, s7, v195
	v_readlane_b32 s101, v39, 3
	v_fma_f32 v196, -v193, s98, v196
	v_readlane_b32 s6, v58, 0
	v_fma_f32 v195, -v194, s99, v195
	v_readlane_b32 s7, v59, 0
	v_fma_f32 v196, -v194, s100, v196
	v_readlane_b32 s98, v58, 1
	v_fma_f32 v196, -v195, s101, v196
	v_readlane_b32 s99, v59, 1
	v_fma_f32 v197, -v192, s6, v197
	v_readlane_b32 s100, v58, 2
	v_fma_f32 v198, -v192, s7, v198
	v_readlane_b32 s101, v59, 2
	v_fma_f32 v197, -v193, s98, v197
	v_readlane_b32 s6, v58, 3
	v_fma_f32 v198, -v193, s99, v198
	v_readlane_b32 s7, v59, 3
	v_fma_f32 v197, -v194, s100, v197
	v_readlane_b32 s98, v58, 4
	v_fma_f32 v198, -v194, s101, v198
	v_readlane_b32 s99, v59, 4
	v_fma_f32 v197, -v195, s6, v197
	v_readlane_b32 s100, v59, 5
	v_fma_f32 v198, -v195, s7, v198
	v_readlane_b32 s101, v60, 0
	v_fma_f32 v197, -v196, s98, v197
	v_readlane_b32 s6, v61, 0
	v_fma_f32 v198, -v196, s99, v198
	v_readlane_b32 s7, v60, 1
	v_fma_f32 v198, -v197, s100, v198
	v_readlane_b32 s98, v61, 1
	v_fma_f32 v199, -v192, s101, v199
	v_readlane_b32 s99, v60, 2
	v_fma_f32 v200, -v192, s6, v200
	v_readlane_b32 s100, v61, 2
	v_fma_f32 v199, -v193, s7, v199
	v_readlane_b32 s101, v60, 3
	v_fma_f32 v200, -v193, s98, v200
	v_readlane_b32 s6, v61, 3
	v_fma_f32 v199, -v194, s99, v199
	v_readlane_b32 s7, v60, 4
	v_fma_f32 v200, -v194, s100, v200
	v_readlane_b32 s98, v61, 4
	v_fma_f32 v199, -v195, s101, v199
	v_readlane_b32 s99, v60, 5
	v_fma_f32 v200, -v195, s6, v200
	v_readlane_b32 s100, v61, 5
	v_fma_f32 v199, -v196, s7, v199
	v_readlane_b32 s101, v60, 6
	v_fma_f32 v200, -v196, s98, v200
	v_readlane_b32 s6, v61, 6
	v_fma_f32 v199, -v197, s99, v199
	v_readlane_b32 s7, v61, 7
	v_fma_f32 v200, -v197, s100, v200
	v_readlane_b32 s98, v230, 0
	v_fma_f32 v199, -v198, s101, v199
	v_readlane_b32 s99, v231, 0
	v_fma_f32 v200, -v198, s6, v200
	v_readlane_b32 s100, v230, 1
	v_fma_f32 v200, -v199, s7, v200
	v_readlane_b32 s101, v231, 1
	v_fma_f32 v201, -v192, s98, v201
	v_readlane_b32 s6, v230, 2
	v_fma_f32 v202, -v192, s99, v202
	v_readlane_b32 s7, v231, 2
	v_fma_f32 v201, -v193, s100, v201
	v_readlane_b32 s98, v230, 3
	v_fma_f32 v202, -v193, s101, v202
	v_readlane_b32 s99, v231, 3
	v_fma_f32 v201, -v194, s6, v201
	v_readlane_b32 s100, v230, 4
	v_fma_f32 v202, -v194, s7, v202
	v_readlane_b32 s101, v231, 4
	v_fma_f32 v201, -v195, s98, v201
	v_readlane_b32 s6, v230, 5
	v_fma_f32 v202, -v195, s99, v202
	v_readlane_b32 s7, v231, 5
	v_fma_f32 v201, -v196, s100, v201
	v_readlane_b32 s98, v230, 6
	v_fma_f32 v202, -v196, s101, v202
	v_readlane_b32 s99, v231, 6
	v_fma_f32 v201, -v197, s6, v201
	v_readlane_b32 s100, v230, 7
	v_fma_f32 v202, -v197, s7, v202
	v_readlane_b32 s101, v231, 7
	v_fma_f32 v201, -v198, s98, v201
	v_readlane_b32 s6, v230, 8
	v_fma_f32 v202, -v198, s99, v202
	v_readlane_b32 s7, v231, 8
	v_fma_f32 v201, -v199, s100, v201
	v_readlane_b32 s98, v231, 9
	v_fma_f32 v202, -v199, s101, v202
	v_readlane_b32 s99, v232, 0
	v_fma_f32 v201, -v200, s6, v201
	v_readlane_b32 s100, v233, 0
	v_fma_f32 v202, -v200, s7, v202
	v_readlane_b32 s101, v232, 1
	v_fma_f32 v202, -v201, s98, v202
	v_readlane_b32 s6, v233, 1
	v_fma_f32 v203, -v192, s99, v203
	v_readlane_b32 s7, v232, 2
	v_fma_f32 v204, -v192, s100, v204
; DI void phase_gdn_prep(const Params& p, int l, char* smem) {
;     ...
;         for (int rb = 0; rb < 4; ++rb) {
;             if (rb > 0) {
;                 const int j = tid & 127, rh = tid >> 7;
;                 float* X = (j < 64) ? sv : sk; const int col = j & 63;
;                 const int r0 = rb * 16 + rh * 8;
;                 float a[8];
; #pragma unroll
;                 for (int i = 0; i < 8; ++i) a[i] = 0.f;
;                 for (int s4 = 0; s4 < rb * 16; s4 += 4) {
;                     const float x0 = X[(s4 + 0) * 65 + col], x1 = X[(s4 + 1) * 65 + col], x2 = X[(s4 + 2) * 65 + col], x3 = X[(s4 + 3) * 65 + col];
; #pragma unroll
;                     for (int i = 0; i < 8; ++i) {
;                         const f32x4 lv = *(const f32x4*)(sL + (r0 + i) * 64 + s4);
;                         a[i] += lv[0] * x0 + lv[1] * x1 + lv[2] * x2 + lv[3] * x3;
;                     }
;                 }
; #pragma unroll
;                 for (int i = 0; i < 8; ++i) X[(r0 + i) * 65 + col] -= a[i];
;                 __syncthreads();
;             }
;             if (tid < 128) {
;                 float* X = (tid < 64) ? sv : sk; const int col = tid & 63;
;                 float x[16];
; #pragma unroll
;                 for (int i = 0; i < 16; ++i) x[i] = X[(rb * 16 + i) * 65 + col];
; #pragma unroll
;                 for (int i = 1; i < 16; ++i) {
;                     const float* Lr = sL + (rb * 16 + i) * 64 + rb * 16;
;                     float acc = x[i];
; #pragma unroll
;                     for (int s2 = 0; s2 < i; ++s2) acc -= Lr[s2] * x[s2];
;                     x[i] = acc;
;                 }
; #pragma unroll
;                 for (int i = 1; i < 16; ++i) X[(rb * 16 + i) * 65 + col] = x[i];
;             }
;             __syncthreads();
;         }
	v_readlane_b32 s98, v233, 2
	v_fma_f32 v203, -v193, s101, v203
	v_readlane_b32 s99, v232, 3
	v_fma_f32 v204, -v193, s6, v204
	v_readlane_b32 s100, v233, 3
	v_fma_f32 v203, -v194, s7, v203
	v_readlane_b32 s101, v232, 4
	v_fma_f32 v204, -v194, s98, v204
	v_readlane_b32 s6, v233, 4
	v_fma_f32 v203, -v195, s99, v203
	v_readlane_b32 s7, v232, 5
	v_fma_f32 v204, -v195, s100, v204
	v_readlane_b32 s98, v233, 5
	v_fma_f32 v203, -v196, s101, v203
	v_readlane_b32 s99, v232, 6
	v_fma_f32 v204, -v196, s6, v204
	v_readlane_b32 s100, v233, 6
	v_fma_f32 v203, -v197, s7, v203
	v_readlane_b32 s101, v232, 7
	v_fma_f32 v204, -v197, s98, v204
	v_readlane_b32 s6, v233, 7
	v_fma_f32 v203, -v198, s99, v203
	v_readlane_b32 s7, v232, 8
	v_fma_f32 v204, -v198, s100, v204
	v_readlane_b32 s98, v233, 8
	v_fma_f32 v203, -v199, s101, v203
	v_readlane_b32 s99, v232, 9
	v_fma_f32 v204, -v199, s6, v204
	v_readlane_b32 s100, v233, 9
	v_fma_f32 v203, -v200, s7, v203
	v_readlane_b32 s101, v232, 10
	v_fma_f32 v204, -v200, s98, v204
	v_readlane_b32 s6, v233, 10
	v_fma_f32 v203, -v201, s99, v203
	v_readlane_b32 s7, v233, 11
	v_fma_f32 v204, -v201, s100, v204
	v_readlane_b32 s98, v234, 0
	v_fma_f32 v203, -v202, s101, v203
	v_readlane_b32 s99, v235, 0
	v_fma_f32 v204, -v202, s6, v204
	v_readlane_b32 s100, v234, 1
	v_fma_f32 v204, -v203, s7, v204
	v_readlane_b32 s101, v235, 1
	v_fma_f32 v205, -v192, s98, v205
	v_readlane_b32 s6, v234, 2
	v_fma_f32 v206, -v192, s99, v206
	v_readlane_b32 s7, v235, 2
	v_fma_f32 v205, -v193, s100, v205
	v_readlane_b32 s98, v234, 3
	v_fma_f32 v206, -v193, s101, v206
	v_readlane_b32 s99, v235, 3
	v_fma_f32 v205, -v194, s6, v205
	v_readlane_b32 s100, v234, 4
	v_fma_f32 v206, -v194, s7, v206
	v_readlane_b32 s101, v235, 4
	v_fma_f32 v205, -v195, s98, v205
	v_readlane_b32 s6, v234, 5
	v_fma_f32 v206, -v195, s99, v206
	v_readlane_b32 s7, v235, 5
	v_fma_f32 v205, -v196, s100, v205
	v_readlane_b32 s98, v234, 6
	v_fma_f32 v206, -v196, s101, v206
	v_readlane_b32 s99, v235, 6
	v_fma_f32 v205, -v197, s6, v205
	v_readlane_b32 s100, v234, 7
	v_fma_f32 v206, -v197, s7, v206
	v_readlane_b32 s101, v235, 7
	v_fma_f32 v205, -v198, s98, v205
	v_readlane_b32 s6, v234, 8
	v_fma_f32 v206, -v198, s99, v206
	v_readlane_b32 s7, v235, 8
	v_fma_f32 v205, -v199, s100, v205
	v_readlane_b32 s98, v234, 9
	v_fma_f32 v206, -v199, s101, v206
	v_readlane_b32 s99, v235, 9
	v_fma_f32 v205, -v200, s6, v205
	v_readlane_b32 s100, v234, 10
	v_fma_f32 v206, -v200, s7, v206
	v_readlane_b32 s101, v235, 10
	v_fma_f32 v205, -v201, s98, v205
	v_readlane_b32 s6, v234, 11
	v_fma_f32 v206, -v201, s99, v206
	v_readlane_b32 s7, v235, 11
	v_fma_f32 v205, -v202, s100, v205
	v_readlane_b32 s98, v234, 12
	v_fma_f32 v206, -v202, s101, v206
	v_readlane_b32 s99, v235, 12
	v_fma_f32 v205, -v203, s6, v205
	v_readlane_b32 s100, v235, 13
	v_fma_f32 v206, -v203, s7, v206
	v_readlane_b32 s101, v236, 0
	v_fma_f32 v205, -v204, s98, v205
	v_readlane_b32 s6, v236, 1
	v_fma_f32 v206, -v204, s99, v206
	v_readlane_b32 s7, v236, 2
	v_fma_f32 v206, -v205, s100, v206
	v_readlane_b32 s98, v236, 3
	v_fma_f32 v207, -v192, s101, v207
	v_readlane_b32 s99, v236, 4
	v_fma_f32 v207, -v193, s6, v207
	v_readlane_b32 s100, v236, 5
	v_fma_f32 v207, -v194, s7, v207
	v_readlane_b32 s101, v236, 6
	v_fma_f32 v207, -v195, s98, v207
	v_readlane_b32 s6, v236, 7
	v_fma_f32 v207, -v196, s99, v207
	v_readlane_b32 s7, v236, 8
	v_fma_f32 v207, -v197, s100, v207
	v_readlane_b32 s98, v236, 9
	v_fma_f32 v207, -v198, s101, v207
	v_readlane_b32 s99, v236, 10
	v_fma_f32 v207, -v199, s6, v207
	v_readlane_b32 s100, v236, 11
	v_fma_f32 v207, -v200, s7, v207
	v_readlane_b32 s101, v236, 12
	v_fma_f32 v207, -v201, s98, v207
	v_readlane_b32 s6, v236, 13
	v_fma_f32 v207, -v202, s99, v207
	v_readlane_b32 s7, v236, 14
	v_fma_f32 v207, -v203, s100, v207
	v_fma_f32 v207, -v204, s101, v207
	v_fma_f32 v207, -v205, s6, v207
	v_fma_f32 v207, -v206, s7, v207
	v_lshlrev_b32_e32 v186, 10, v185
	v_lshl_add_u32 v186, v191, 2, v186
	ds_write_b32 v186, v192 offset:0
	ds_write_b32 v186, v193 offset:64
	ds_write_b32 v186, v194 offset:128
	ds_write_b32 v186, v195 offset:192
	ds_write_b32 v186, v196 offset:256
	ds_write_b32 v186, v197 offset:320
	ds_write_b32 v186, v198 offset:384
	ds_write_b32 v186, v199 offset:448
	ds_write_b32 v186, v200 offset:512
	ds_write_b32 v186, v201 offset:576
	ds_write_b32 v186, v202 offset:640
	ds_write_b32 v186, v203 offset:704
	ds_write_b32 v186, v204 offset:768
	ds_write_b32 v186, v205 offset:832
	ds_write_b32 v186, v206 offset:896
	ds_write_b32 v186, v207 offset:960
	v_lshlrev_b32_e32 v188, 6, v191
	v_lshl_add_u32 v188, v208, 4, v188
	v_lshlrev_b32_e32 v209, 8, v191
	v_lshl_add_u32 v209, v208, 4, v209
	v_add_u32_e32 v209, 0xc300, v209
	v_mul_u32_u24_e32 v187, 0x410, v208
	v_lshl_add_u32 v187, v191, 2, v187
	v_and_b32_e32 v243, 64, v40
	v_lshl_add_u32 v187, v243, 1, v187
	v_mov_b32_e32 v243, 0x8200
	v_mov_b32_e32 v244, 0x4100
	s_nop 0
	v_cndmask_b32_e64 v243, v244, v243, s[48:49]
	v_add_u32_e32 v187, v187, v243
	s_waitcnt lgkmcnt(0)
	s_barrier
; DI void phase_gdn_prep(const Params& p, int l, char* smem) {
;     ...
;         for (int rb = 0; rb < 4; ++rb) {
;             if (rb > 0) {
;                 const int j = tid & 127, rh = tid >> 7;
;                 float* X = (j < 64) ? sv : sk; const int col = j & 63;
;                 const int r0 = rb * 16 + rh * 8;
;                 float a[8];
; #pragma unroll
;                 for (int i = 0; i < 8; ++i) a[i] = 0.f;
;                 for (int s4 = 0; s4 < rb * 16; s4 += 4) {
;                     const float x0 = X[(s4 + 0) * 65 + col], x1 = X[(s4 + 1) * 65 + col], x2 = X[(s4 + 2) * 65 + col], x3 = X[(s4 + 3) * 65 + col];
; #pragma unroll
;                     for (int i = 0; i < 8; ++i) {
;                         const f32x4 lv = *(const f32x4*)(sL + (r0 + i) * 64 + s4);
;                         a[i] += lv[0] * x0 + lv[1] * x1 + lv[2] * x2 + lv[3] * x3;
;                     }
;                 }
; #pragma unroll
;                 for (int i = 0; i < 8; ++i) X[(r0 + i) * 65 + col] -= a[i];
;                 __syncthreads();
;             }
;             if (tid < 128) {
;                 float* X = (tid < 64) ? sv : sk; const int col = tid & 63;
;                 float x[16];
; #pragma unroll
;                 for (int i = 0; i < 16; ++i) x[i] = X[(rb * 16 + i) * 65 + col];
; #pragma unroll
;                 for (int i = 1; i < 16; ++i) {
;                     const float* Lr = sL + (rb * 16 + i) * 64 + rb * 16;
;                     float acc = x[i];
; #pragma unroll
;                     for (int s2 = 0; s2 < i; ++s2) acc -= Lr[s2] * x[s2];
;                     x[i] = acc;
;                 }
; #pragma unroll
;                 for (int i = 1; i < 16; ++i) X[(rb * 16 + i) * 65 + col] = x[i];
;             }
;             __syncthreads();
;         }
	ds_read_b32 v192, v187 offset:0
	ds_read_b32 v193, v187 offset:260
	ds_read_b32 v194, v187 offset:520
	ds_read_b32 v195, v187 offset:780
	ds_read_b32 v196, v187 offset:4160
	ds_read_b32 v197, v187 offset:4420
	ds_read_b32 v198, v187 offset:4680
	ds_read_b32 v199, v187 offset:4940
	ds_read_b32 v200, v187 offset:8320
	ds_read_b32 v201, v187 offset:8580
	ds_read_b32 v202, v187 offset:8840
	ds_read_b32 v203, v187 offset:9100
	ds_read_b32 v204, v187 offset:12480
	ds_read_b32 v205, v187 offset:12740
	ds_read_b32 v206, v187 offset:13000
	ds_read_b32 v207, v187 offset:13260
	ds_read_b128 v[36:39], v188 offset:0
	s_waitcnt lgkmcnt(0)
	v_mfma_f32_16x16x4_f32 v[230:233], v36, v192, 0
	v_mfma_f32_16x16x4_f32 v[230:233], v37, v193, v[230:233]
	v_mfma_f32_16x16x4_f32 v[230:233], v38, v194, v[230:233]
	v_mfma_f32_16x16x4_f32 v[230:233], v39, v195, v[230:233]
	s_nop 7
	s_nop 2
	v_mov_b32_e32 v192, v230
	v_mov_b32_e32 v193, v231
	v_mov_b32_e32 v194, v232
	v_mov_b32_e32 v195, v233
	s_nop 7
	s_nop 2
	ds_read_b128 v[36:39], v188 offset:1024
	ds_read_b128 v[58:61], v209 offset:4096
	s_waitcnt lgkmcnt(0)
	v_mfma_f32_16x16x4_f32 v[230:233], v58, v192, 0
	v_mfma_f32_16x16x4_f32 v[230:233], v59, v193, v[230:233]
	v_mfma_f32_16x16x4_f32 v[230:233], v60, v194, v[230:233]
	v_mfma_f32_16x16x4_f32 v[230:233], v61, v195, v[230:233]
	s_nop 7
	s_nop 2
	v_sub_f32_e32 v230, v196, v230
	v_sub_f32_e32 v231, v197, v231
	v_sub_f32_e32 v232, v198, v232
	v_sub_f32_e32 v233, v199, v233
	s_nop 1
	v_mfma_f32_16x16x4_f32 v[196:199], v36, v230, 0
	v_mfma_f32_16x16x4_f32 v[196:199], v37, v231, v[196:199]
	v_mfma_f32_16x16x4_f32 v[196:199], v38, v232, v[196:199]
	v_mfma_f32_16x16x4_f32 v[196:199], v39, v233, v[196:199]
	s_nop 7
	s_nop 2
	ds_read_b128 v[36:39], v188 offset:2048
	ds_read_b128 v[58:61], v209 offset:8192
	ds_read_b128 v[234:237], v209 offset:8256
	s_waitcnt lgkmcnt(0)
	v_mfma_f32_16x16x4_f32 v[230:233], v58, v192, 0
	v_mfma_f32_16x16x4_f32 v[230:233], v59, v193, v[230:233]
	v_mfma_f32_16x16x4_f32 v[230:233], v60, v194, v[230:233]
	v_mfma_f32_16x16x4_f32 v[230:233], v61, v195, v[230:233]
	v_mfma_f32_16x16x4_f32 v[230:233], v234, v196, v[230:233]
	v_mfma_f32_16x16x4_f32 v[230:233], v235, v197, v[230:233]
	v_mfma_f32_16x16x4_f32 v[230:233], v236, v198, v[230:233]
	v_mfma_f32_16x16x4_f32 v[230:233], v237, v199, v[230:233]
	s_nop 7
	s_nop 2
	v_sub_f32_e32 v230, v200, v230
	v_sub_f32_e32 v231, v201, v231
	v_sub_f32_e32 v232, v202, v232
	v_sub_f32_e32 v233, v203, v233
	s_nop 1
	v_mfma_f32_16x16x4_f32 v[200:203], v36, v230, 0
	v_mfma_f32_16x16x4_f32 v[200:203], v37, v231, v[200:203]
	v_mfma_f32_16x16x4_f32 v[200:203], v38, v232, v[200:203]
	v_mfma_f32_16x16x4_f32 v[200:203], v39, v233, v[200:203]
	s_nop 7
	s_nop 2
	ds_read_b128 v[36:39], v188 offset:3072
	ds_read_b128 v[58:61], v209 offset:12288
	ds_read_b128 v[234:237], v209 offset:12352
	ds_read_b128 v[238:241], v209 offset:12416
	s_waitcnt lgkmcnt(0)
	v_mfma_f32_16x16x4_f32 v[230:233], v58, v192, 0
	v_mfma_f32_16x16x4_f32 v[230:233], v59, v193, v[230:233]
	v_mfma_f32_16x16x4_f32 v[230:233], v60, v194, v[230:233]
	v_mfma_f32_16x16x4_f32 v[230:233], v61, v195, v[230:233]
	v_mfma_f32_16x16x4_f32 v[230:233], v234, v196, v[230:233]
	v_mfma_f32_16x16x4_f32 v[230:233], v235, v197, v[230:233]
	v_mfma_f32_16x16x4_f32 v[230:233], v236, v198, v[230:233]
	v_mfma_f32_16x16x4_f32 v[230:233], v237, v199, v[230:233]
	v_mfma_f32_16x16x4_f32 v[230:233], v238, v200, v[230:233]
	v_mfma_f32_16x16x4_f32 v[230:233], v239, v201, v[230:233]
	v_mfma_f32_16x16x4_f32 v[230:233], v240, v202, v[230:233]
	v_mfma_f32_16x16x4_f32 v[230:233], v241, v203, v[230:233]
	s_nop 7
	s_nop 2
	v_sub_f32_e32 v230, v204, v230
	v_sub_f32_e32 v231, v205, v231
	v_sub_f32_e32 v232, v206, v232
	v_sub_f32_e32 v233, v207, v233
	s_nop 1
	v_mfma_f32_16x16x4_f32 v[204:207], v36, v230, 0
	v_mfma_f32_16x16x4_f32 v[204:207], v37, v231, v[204:207]
	v_mfma_f32_16x16x4_f32 v[204:207], v38, v232, v[204:207]
	v_mfma_f32_16x16x4_f32 v[204:207], v39, v233, v[204:207]
	s_nop 7
	s_nop 2
	ds_write_b32 v187, v192 offset:0
	ds_write_b32 v187, v193 offset:260
	ds_write_b32 v187, v194 offset:520
	ds_write_b32 v187, v195 offset:780
	ds_write_b32 v187, v196 offset:4160
	ds_write_b32 v187, v197 offset:4420
	ds_write_b32 v187, v198 offset:4680
	ds_write_b32 v187, v199 offset:4940
	ds_write_b32 v187, v200 offset:8320
	ds_write_b32 v187, v201 offset:8580
	ds_write_b32 v187, v202 offset:8840
	ds_write_b32 v187, v203 offset:9100
	ds_write_b32 v187, v204 offset:12480
	ds_write_b32 v187, v205 offset:12740
	ds_write_b32 v187, v206 offset:13000
	ds_write_b32 v187, v207 offset:13260
	ds_read_b32 v192, v187 offset:64
	ds_read_b32 v193, v187 offset:324
	ds_read_b32 v194, v187 offset:584
	ds_read_b32 v195, v187 offset:844
	ds_read_b32 v196, v187 offset:4224
	ds_read_b32 v197, v187 offset:4484
	ds_read_b32 v198, v187 offset:4744
	ds_read_b32 v199, v187 offset:5004
	ds_read_b32 v200, v187 offset:8384
	ds_read_b32 v201, v187 offset:8644
	ds_read_b32 v202, v187 offset:8904
	ds_read_b32 v203, v187 offset:9164
	ds_read_b32 v204, v187 offset:12544
	ds_read_b32 v205, v187 offset:12804
	ds_read_b32 v206, v187 offset:13064
	ds_read_b32 v207, v187 offset:13324
	ds_read_b128 v[36:39], v188 offset:0
	s_waitcnt lgkmcnt(0)
; DI void phase_gdn_prep(const Params& p, int l, char* smem) {
;     ...
;         for (int rb = 0; rb < 4; ++rb) {
;             if (rb > 0) {
;                 const int j = tid & 127, rh = tid >> 7;
;                 float* X = (j < 64) ? sv : sk; const int col = j & 63;
;                 const int r0 = rb * 16 + rh * 8;
;                 float a[8];
; #pragma unroll
;                 for (int i = 0; i < 8; ++i) a[i] = 0.f;
;                 for (int s4 = 0; s4 < rb * 16; s4 += 4) {
;                     const float x0 = X[(s4 + 0) * 65 + col], x1 = X[(s4 + 1) * 65 + col], x2 = X[(s4 + 2) * 65 + col], x3 = X[(s4 + 3) * 65 + col];
; #pragma unroll
;                     for (int i = 0; i < 8; ++i) {
;                         const f32x4 lv = *(const f32x4*)(sL + (r0 + i) * 64 + s4);
;                         a[i] += lv[0] * x0 + lv[1] * x1 + lv[2] * x2 + lv[3] * x3;
;                     }
;                 }
; #pragma unroll
;                 for (int i = 0; i < 8; ++i) X[(r0 + i) * 65 + col] -= a[i];
;                 __syncthreads();
;             }
;             if (tid < 128) {
;                 float* X = (tid < 64) ? sv : sk; const int col = tid & 63;
;                 float x[16];
; #pragma unroll
;                 for (int i = 0; i < 16; ++i) x[i] = X[(rb * 16 + i) * 65 + col];
; #pragma unroll
;                 for (int i = 1; i < 16; ++i) {
;                     const float* Lr = sL + (rb * 16 + i) * 64 + rb * 16;
;                     float acc = x[i];
; #pragma unroll
;                     for (int s2 = 0; s2 < i; ++s2) acc -= Lr[s2] * x[s2];
;                     x[i] = acc;
;                 }
; #pragma unroll
;                 for (int i = 1; i < 16; ++i) X[(rb * 16 + i) * 65 + col] = x[i];
;             }
;             __syncthreads();
;         }
	v_mfma_f32_16x16x4_f32 v[230:233], v36, v192, 0
	v_mfma_f32_16x16x4_f32 v[230:233], v37, v193, v[230:233]
	v_mfma_f32_16x16x4_f32 v[230:233], v38, v194, v[230:233]
	v_mfma_f32_16x16x4_f32 v[230:233], v39, v195, v[230:233]
	s_nop 7
	s_nop 2
	v_mov_b32_e32 v192, v230
	v_mov_b32_e32 v193, v231
	v_mov_b32_e32 v194, v232
	v_mov_b32_e32 v195, v233
	s_nop 7
	s_nop 2
	ds_read_b128 v[36:39], v188 offset:1024
	ds_read_b128 v[58:61], v209 offset:4096
	s_waitcnt lgkmcnt(0)
	v_mfma_f32_16x16x4_f32 v[230:233], v58, v192, 0
	v_mfma_f32_16x16x4_f32 v[230:233], v59, v193, v[230:233]
	v_mfma_f32_16x16x4_f32 v[230:233], v60, v194, v[230:233]
	v_mfma_f32_16x16x4_f32 v[230:233], v61, v195, v[230:233]
	s_nop 7
	s_nop 2
	v_sub_f32_e32 v230, v196, v230
	v_sub_f32_e32 v231, v197, v231
	v_sub_f32_e32 v232, v198, v232
	v_sub_f32_e32 v233, v199, v233
	s_nop 1
	v_mfma_f32_16x16x4_f32 v[196:199], v36, v230, 0
	v_mfma_f32_16x16x4_f32 v[196:199], v37, v231, v[196:199]
	v_mfma_f32_16x16x4_f32 v[196:199], v38, v232, v[196:199]
	v_mfma_f32_16x16x4_f32 v[196:199], v39, v233, v[196:199]
	s_nop 7
	s_nop 2
	ds_read_b128 v[36:39], v188 offset:2048
	ds_read_b128 v[58:61], v209 offset:8192
	ds_read_b128 v[234:237], v209 offset:8256
	s_waitcnt lgkmcnt(0)
	v_mfma_f32_16x16x4_f32 v[230:233], v58, v192, 0
	v_mfma_f32_16x16x4_f32 v[230:233], v59, v193, v[230:233]
	v_mfma_f32_16x16x4_f32 v[230:233], v60, v194, v[230:233]
	v_mfma_f32_16x16x4_f32 v[230:233], v61, v195, v[230:233]
	v_mfma_f32_16x16x4_f32 v[230:233], v234, v196, v[230:233]
	v_mfma_f32_16x16x4_f32 v[230:233], v235, v197, v[230:233]
	v_mfma_f32_16x16x4_f32 v[230:233], v236, v198, v[230:233]
	v_mfma_f32_16x16x4_f32 v[230:233], v237, v199, v[230:233]
	s_nop 7
	s_nop 2
	v_sub_f32_e32 v230, v200, v230
	v_sub_f32_e32 v231, v201, v231
	v_sub_f32_e32 v232, v202, v232
	v_sub_f32_e32 v233, v203, v233
	s_nop 1
	v_mfma_f32_16x16x4_f32 v[200:203], v36, v230, 0
	v_mfma_f32_16x16x4_f32 v[200:203], v37, v231, v[200:203]
	v_mfma_f32_16x16x4_f32 v[200:203], v38, v232, v[200:203]
	v_mfma_f32_16x16x4_f32 v[200:203], v39, v233, v[200:203]
	s_nop 7
	s_nop 2
	ds_read_b128 v[36:39], v188 offset:3072
	ds_read_b128 v[58:61], v209 offset:12288
	ds_read_b128 v[234:237], v209 offset:12352
	ds_read_b128 v[238:241], v209 offset:12416
	s_waitcnt lgkmcnt(0)
	v_mfma_f32_16x16x4_f32 v[230:233], v58, v192, 0
	v_mfma_f32_16x16x4_f32 v[230:233], v59, v193, v[230:233]
	v_mfma_f32_16x16x4_f32 v[230:233], v60, v194, v[230:233]
	v_mfma_f32_16x16x4_f32 v[230:233], v61, v195, v[230:233]
	v_mfma_f32_16x16x4_f32 v[230:233], v234, v196, v[230:233]
	v_mfma_f32_16x16x4_f32 v[230:233], v235, v197, v[230:233]
	v_mfma_f32_16x16x4_f32 v[230:233], v236, v198, v[230:233]
	v_mfma_f32_16x16x4_f32 v[230:233], v237, v199, v[230:233]
	v_mfma_f32_16x16x4_f32 v[230:233], v238, v200, v[230:233]
	v_mfma_f32_16x16x4_f32 v[230:233], v239, v201, v[230:233]
	v_mfma_f32_16x16x4_f32 v[230:233], v240, v202, v[230:233]
	v_mfma_f32_16x16x4_f32 v[230:233], v241, v203, v[230:233]
	s_nop 7
	s_nop 2
	v_sub_f32_e32 v230, v204, v230
	v_sub_f32_e32 v231, v205, v231
	v_sub_f32_e32 v232, v206, v232
	v_sub_f32_e32 v233, v207, v233
	s_nop 1
	v_mfma_f32_16x16x4_f32 v[204:207], v36, v230, 0
	v_mfma_f32_16x16x4_f32 v[204:207], v37, v231, v[204:207]
	v_mfma_f32_16x16x4_f32 v[204:207], v38, v232, v[204:207]
	v_mfma_f32_16x16x4_f32 v[204:207], v39, v233, v[204:207]
	s_nop 7
	s_nop 2
	ds_write_b32 v187, v192 offset:64
	ds_write_b32 v187, v193 offset:324
	ds_write_b32 v187, v194 offset:584
	ds_write_b32 v187, v195 offset:844
	ds_write_b32 v187, v196 offset:4224
	ds_write_b32 v187, v197 offset:4484
	ds_write_b32 v187, v198 offset:4744
	ds_write_b32 v187, v199 offset:5004
	ds_write_b32 v187, v200 offset:8384
	ds_write_b32 v187, v201 offset:8644
	ds_write_b32 v187, v202 offset:8904
	ds_write_b32 v187, v203 offset:9164
	ds_write_b32 v187, v204 offset:12544
	ds_write_b32 v187, v205 offset:12804
	ds_write_b32 v187, v206 offset:13064
	ds_write_b32 v187, v207 offset:13324
	s_waitcnt lgkmcnt(0)
	s_barrier
	s_branch .LBB0_263
